# spatial-gating items regrouped so the four items sharing a LayerNorm row block run on one XCD (workgroup id mod 8)
# baseline (speedup 1.0000x reference)
; __device__ __forceinline__ int tid_opaque() { int t = threadIdx.x; asm volatile("" : "+v"(t)); return t; }
; __device__ __forceinline__ void mix_sgu(const bf16* h, const float* lng, const float* lnb, const float* sgw, const float* sgb, bf16* ycat, char* lds, int wg, int nwg) {
;     typedef _Float16 sbf16x8 __attribute__((ext_vector_type(8)));
;     const int tid = tid_opaque(), lane = tid & 63, wid = __builtin_amdgcn_readfirstlane(tid >> 6), li = lane & 15, g = lane >> 4;
;     for (int item = wg; item < NB * 32 * 4; item += nwg) {
;         const int grp = item & 3, n = (item >> 2) & 31, b = item >> 7;
;         const size_t m0 = (size_t)b * SEQ + n * 128;
; #pragma unroll
;         for (int i = 0; i < 8; ++i) { const int idx = tid + 512 * i, t = idx >> 5, s4 = (idx & 31) * 4; const f32x4 w = *(const f32x4*)(sgw + (size_t)grp * 16384 + t * 128 + s4);
;             typedef _Float16 h4 __attribute__((ext_vector_type(4))); h4 o; o[0] = (_Float16)(s4 <= t ? w[0] : 0.f); o[1] = (_Float16)(s4 + 1 <= t ? w[1] : 0.f); o[2] = (_Float16)(s4 + 2 <= t ? w[2] : 0.f); o[3] = (_Float16)(s4 + 3 <= t ? w[3] : 0.f); *(h4*)(lds + t * 288 + s4 * 2) = o; }
;         { const int row = tid >> 2, q = tid & 3; const bf16* vr = h + (m0 + row) * NH + C_DV;
.LBB0_673:
	s_or_b64 exec, exec, s[0:1]
	v_readlane_b32 s0, v255, 50
	s_mov_b64 s[38:39], s[20:21]
	v_mov_b32_e32 v0, v252
	v_readlane_b32 s1, v255, 51
	s_and_b64 vcc, exec, s[0:1]
	v_readfirstlane_b32 s4, v0
	s_cbranch_vccnz .LBB0_680
	s_add_u32 s0, s38, 0xa800000
	s_addc_u32 s1, s39, 0
	s_lshl_b64 s[2:3], s[6:7], 2
	v_readlane_b32 s40, v253, 18
	v_readlane_b32 s41, v253, 19
	s_add_u32 s36, s40, s2
	v_readlane_b32 s42, v253, 20
	s_addc_u32 s37, s41, s3
	v_writelane_b32 v255, s94, 52
	v_readlane_b32 s43, v253, 21
	s_add_u32 s14, s42, s2
	v_writelane_b32 v255, s95, 53
	v_readlane_b32 s46, v253, 24
	s_addc_u32 s15, s43, s3
	v_readlane_b32 s47, v253, 25
	s_add_u32 s2, s46, s2
	v_readlane_b32 s6, v255, 45
	s_addc_u32 s3, s47, s3
	v_readlane_b32 s7, v255, 46
	s_lshl_b32 s28, s6, 16
	v_readlane_b32 s44, v253, 22
	s_lshl_b64 s[6:7], s[28:29], 2
	v_lshlrev_b32_e32 v2, 2, v0
	v_readlane_b32 s45, v253, 23
	s_add_u32 s6, s44, s6
	v_and_b32_e32 v5, 0x7c, v2
	v_and_b32_e32 v10, 64, v223
	s_addc_u32 s7, s45, s7
	v_lshlrev_b32_e32 v168, 2, v5
	v_xor_b32_e32 v4, 1, v223
	v_add_u32_e32 v10, 64, v10
	s_ashr_i32 s5, s4, 2
	s_ashr_i32 s4, s4, 31
	v_lshl_add_u64 v[32:33], s[6:7], 0, v[168:169]
	v_cmp_lt_i32_e32 vcc, v4, v10
	s_or_b32 s6, s5, 15
	s_lshr_b32 s4, s4, 27
	v_cndmask_b32_e32 v4, v223, v4, vcc
	s_add_i32 s4, s6, s4
	v_lshlrev_b32_e32 v37, 2, v4
	v_xor_b32_e32 v4, 2, v223
	s_ashr_i32 s4, s4, 5
	v_cmp_lt_i32_e32 vcc, v4, v10
	s_cmpk_gt_i32 s6, 0xffe0
	v_bfe_u32 v3, v0, 4, 2
	v_cndmask_b32_e32 v4, v223, v4, vcc
	s_cselect_b64 s[6:7], -1, 0
	v_lshlrev_b32_e32 v64, 2, v4
	v_writelane_b32 v255, s6, 54
	v_lshlrev_b32_e32 v11, 4, v3
	v_lshlrev_b32_e32 v4, 2, v3
	v_ashrrev_i32_e32 v3, 5, v0
	v_writelane_b32 v255, s7, 55
	v_cmp_gt_i32_e64 s[6:7], v5, v3
	v_and_b32_e32 v9, 3, v0
	v_and_b32_e32 v1, 15, v0
	v_writelane_b32 v255, s6, 56
	v_ashrrev_i32_e32 v34, 2, v0
	v_lshlrev_b32_e32 v36, 5, v9
	v_writelane_b32 v255, s7, 57
	v_cmp_lt_i32_e64 s[6:7], v5, v3
	v_bfi_b32 v38, -16, s5, v0
	v_add_u32_e32 v12, 0x200, v0
	v_writelane_b32 v255, s6, 58
	v_add_u32_e32 v13, 0x400, v0
	v_add_u32_e32 v14, 0x600, v0
	v_writelane_b32 v255, s7, 59
	v_add_u32_e32 v15, 0x800, v0
	v_add_u32_e32 v16, 0xa00, v0
	v_add_u32_e32 v17, 0xc00, v0
	v_add_u32_e32 v0, 0xe00, v0
	s_lshr_b32 s5, s5, 4
	s_add_i32 s4, s4, 1
	v_readlane_b32 s48, v253, 26
	v_readlane_b32 s49, v253, 27
	v_readlane_b32 s50, v253, 28
	v_readlane_b32 s51, v253, 29
	v_readlane_b32 s52, v253, 30
	v_readlane_b32 s53, v253, 31
	v_readlane_b32 s54, v253, 32
	v_readlane_b32 s55, v253, 33
	v_or_b32_e32 v6, 2, v5
	v_or_b32_e32 v7, 3, v5
	s_movk_i32 s8, 0x120
	v_ashrrev_i32_e32 v12, 5, v12
	v_ashrrev_i32_e32 v13, 5, v13
	v_ashrrev_i32_e32 v14, 5, v14
	v_ashrrev_i32_e32 v15, 5, v15
	v_ashrrev_i32_e32 v16, 5, v16
	v_ashrrev_i32_e32 v17, 5, v17
	v_ashrrev_i32_e32 v0, 5, v0
	s_mulk_i32 s5, 0x1200
	v_or_b32_e32 v18, 8, v36
	v_writelane_b32 v255, s4, 60
	v_lshl_add_u32 v8, v5, 1, 0
	v_lshlrev_b32_e32 v2, 3, v9
	v_lshl_add_u32 v10, v34, 1, 0
	v_lshlrev_b32_e32 v40, 7, v3
	v_cmp_gt_i32_e64 s[44:45], v6, v3
	v_cmp_gt_i32_e64 s[46:47], v7, v3
	v_mul_lo_u32 v3, v3, s8
	v_lshlrev_b32_e32 v42, 7, v12
	v_cmp_gt_i32_e64 s[48:49], v5, v12
	v_cmp_lt_i32_e64 s[50:51], v5, v12
	v_cmp_gt_i32_e64 s[52:53], v6, v12
	v_cmp_gt_i32_e64 s[54:55], v7, v12
	v_mul_lo_u32 v12, v12, s8
	v_lshlrev_b32_e32 v44, 7, v13
	v_cmp_gt_i32_e64 s[56:57], v5, v13
	v_cmp_lt_i32_e64 s[58:59], v5, v13
	v_cmp_gt_i32_e64 s[60:61], v6, v13
	v_cmp_gt_i32_e64 s[62:63], v7, v13
	v_mul_lo_u32 v13, v13, s8
	v_lshlrev_b32_e32 v46, 7, v14
	v_cmp_gt_i32_e64 s[64:65], v5, v14
	v_cmp_lt_i32_e64 s[66:67], v5, v14
	v_cmp_gt_i32_e64 s[68:69], v6, v14
	v_cmp_gt_i32_e64 s[70:71], v7, v14
	v_mul_lo_u32 v14, v14, s8
	v_lshlrev_b32_e32 v48, 7, v15
	v_cmp_gt_i32_e64 s[72:73], v5, v15
	v_cmp_lt_i32_e64 s[74:75], v5, v15
	v_cmp_gt_i32_e64 s[76:77], v6, v15
	v_cmp_gt_i32_e64 s[78:79], v7, v15
	v_mul_lo_u32 v15, v15, s8
	v_lshlrev_b32_e32 v50, 7, v16
	v_cmp_gt_i32_e64 s[80:81], v5, v16
	v_cmp_lt_i32_e64 s[82:83], v5, v16
	s_mov_b64 s[6:7], s[96:97]
	v_cmp_gt_i32_e64 s[84:85], v6, v16
	v_cmp_gt_i32_e64 s[42:43], v7, v16
	v_mul_lo_u32 v16, v16, s8
	v_lshlrev_b32_e32 v52, 7, v17
	v_cmp_gt_i32_e64 s[88:89], v5, v17
	v_cmp_lt_i32_e64 s[90:91], v5, v17
	v_cmp_gt_i32_e64 s[92:93], v6, v17
	v_cmp_gt_i32_e64 s[94:95], v7, v17
	v_mul_lo_u32 v17, v17, s8
	v_lshlrev_b32_e32 v54, 7, v0
	v_mad_u32_u24 v1, v1, s8, v11
	s_add_i32 s5, s5, 0
	v_mul_lo_u32 v11, v0, s8
	v_mul_u32_u24_e32 v9, 0x2400, v9
	v_mul_u32_u24_e32 v18, 0x120, v18
	v_readlane_b32 s4, v255, 29
	v_ashrrev_i32_e32 v35, 31, v34
	v_ashrrev_i32_e32 v39, 31, v38
	v_ashrrev_i32_e32 v41, 31, v40
	v_ashrrev_i32_e32 v43, 31, v42
	v_ashrrev_i32_e32 v45, 31, v44
	v_ashrrev_i32_e32 v47, 31, v46
	v_ashrrev_i32_e32 v49, 31, v48
	v_ashrrev_i32_e32 v51, 31, v50
	v_ashrrev_i32_e32 v53, 31, v52
	v_ashrrev_i32_e32 v55, 31, v54
	v_add_u32_e32 v65, s5, v1
	v_cmp_gt_i32_e64 s[96:97], v5, v0
	v_add_u32_e32 v66, s4, v1
	v_add_u32_e32 v67, v8, v3
	v_add_u32_e32 v68, v8, v12
	v_add_u32_e32 v69, v8, v13
	v_add_u32_e32 v70, v8, v14
	v_add_u32_e32 v71, v8, v15
	v_add_u32_e32 v72, v8, v16
	v_add_u32_e32 v73, v8, v17
	v_add_u32_e32 v74, v8, v11
	v_lshlrev_b32_e32 v168, 1, v2
	v_add_u32_e32 v75, v10, v9
	v_add_u32_e32 v76, v10, v18
	v_lshlrev_b32_e32 v56, 1, v4
	s_mov_b32 s26, s6
	s_cmpk_lg_i32 s86, 0x100
	s_cbranch_scc1 .Lsgu_item_done
	s_lshr_b32 s100, s26, 3
	s_and_b32 s101, s26, 7
	s_lshr_b32 s26, s100, 2
	s_lshl_b32 s26, s26, 3
	s_add_i32 s26, s26, s101
	s_lshl_b32 s26, s26, 2
	s_and_b32 s100, s100, 3
	s_or_b32 s26, s26, s100
.Lsgu_item_done:
	v_cmp_lt_i32_e64 s[4:5], v5, v0
	v_cmp_gt_i32_e64 s[6:7], v6, v0
	v_cmp_gt_i32_e64 s[8:9], v7, v0
	s_branch .LBB0_676
